# P0|P1 grid barrier replaced by team seam: P0 rows remapped to the owning panel team, write-through P0 stores, global counter for the W_in copies
# speedup vs baseline: 1.0161x; 1.0085x over previous
; __host__ __device__ __forceinline__ int tile_slot(int pn) { if (pn >= 16) return pn - 12; const int q = pn & 7; if (q >= 6) return (pn >> 3) * 2 + (q - 6); return (pn >> 3) * 6 + q; }
; #define GAS __attribute__((address_space(1)))
; #define LAS __attribute__((address_space(3)))
; #define LDS_WAIT() asm volatile("s_waitcnt lgkmcnt(0)" ::: "memory")
; __device__ __forceinline__ unsigned pk2(float lo, float hi) { const f32x2_t v = {lo, hi}; return __builtin_bit_cast(unsigned, __builtin_convertvector(v, bf16x2_t)); }
; __device__ __forceinline__ void p0_transpose_item(const float* W, int ldw, int src_col0, int k0, bf16_t* WT, int ldk, int dst_row0, int dst_k0, LAS float* scr, int lane) {
; #pragma unroll
;     for (int i = 0; i < 8; ++i) { const int kk = 8 * i + (lane >> 3), n4 = 4 * (lane & 7);
;         const f32x4 w = *(const GAS f32x4*)(W + (size_t)(k0 + kk) * ldw + src_col0 + n4); LAS float* d = scr + kk * 33 + n4; d[0] = w[0]; d[1] = w[1]; d[2] = w[2]; d[3] = w[3]; }
;     LDS_WAIT(); asm volatile("" ::: "memory");
;     const int c = lane & 7;
; #pragma unroll
;     for (int j = 0; j < 4; ++j) { const int n = (lane >> 3) + 8 * j; const LAS float* s = scr + (8 * c) * 33 + n;
;         v4u o; o.x = pk2(s[0 * 33], s[1 * 33]); o.y = pk2(s[2 * 33], s[3 * 33]); o.z = pk2(s[4 * 33], s[5 * 33]); o.w = pk2(s[6 * 33], s[7 * 33]);
;         *(GAS v4u*)(WT + (size_t)(dst_row0 + n) * ldk + dst_k0 + k0 + 8 * c) = o; }
;     LDS_WAIT(); asm volatile("" ::: "memory");
; }
; __global__ void __launch_bounds__(NWAVES * 64, 2) fwd(Args args) {
;     ...
;         for (int it = gw; it < I_IN; it += NGW) { const int kb = it / 192, nb = it % 192, pn = nb >> 3, row = tile_slot(pn) * 256 + (nb & 7) * 32;
;             p0_transpose_item(w_in, PROJW, orig_col(32 * nb), 64 * kb, tile_is_late(pn) ? WING_T : WIN_T, 1024, row, 0, scr, lane); }
.LBB0_20:
	s_lshl_b32 s8, s35, 8
	s_and_b32 s9, s36, 0xe0
	s_or_b32 s35, s8, s9
	s_lshl_b32 s8, s11, 6
	s_and_b32 s9, s33, 48
	s_cmp_eq_u32 s9, 48
	s_cselect_b64 s[36:37], -1, 0
	s_or_b64 s[6:7], s[6:7], s[36:37]
	s_and_b64 s[6:7], s[6:7], exec
	s_cselect_b32 s33, s5, s65
	s_cselect_b32 s36, s84, s64
	s_ashr_i32 s11, s10, 31
	v_lshl_add_u64 v[60:61], s[10:11], 2, v[4:5]
	v_or_b32_e32 v35, s8, v6
	v_mad_i64_i32 v[40:41], s[6:7], v35, s14, v[60:61]
	v_or_b32_e32 v35, s8, v7
	v_mad_i64_i32 v[44:45], s[6:7], v35, s14, v[60:61]
	v_or_b32_e32 v35, s8, v10
	v_or_b32_e32 v30, s8, v8
	v_or_b32_e32 v32, s8, v1
	v_mad_i64_i32 v[48:49], s[6:7], v35, s14, v[60:61]
	v_or_b32_e32 v35, s8, v11
	v_mad_i64_i32 v[30:31], s[6:7], v30, s14, v[60:61]
	v_mad_i64_i32 v[36:37], s[6:7], v32, s14, v[60:61]
	v_mad_i64_i32 v[52:53], s[6:7], v35, s14, v[60:61]
	global_load_dwordx4 v[30:33], v[30:31], off nt
	s_nop 0
	global_load_dwordx4 v[36:39], v[36:37], off nt
	s_nop 0
	global_load_dwordx4 v[40:43], v[40:41], off nt
	s_nop 0
	global_load_dwordx4 v[44:47], v[44:45], off nt
	s_nop 0
	global_load_dwordx4 v[48:51], v[48:49], off nt
	s_nop 0
	global_load_dwordx4 v[52:55], v[52:53], off nt
	v_or_b32_e32 v35, s8, v12
	v_mad_i64_i32 v[56:57], s[6:7], v35, s14, v[60:61]
	global_load_dwordx4 v[56:59], v[56:57], off nt
	v_or_b32_e32 v35, s8, v13
	v_mad_i64_i32 v[60:61], s[6:7], v35, s14, v[60:61]
	global_load_dwordx4 v[60:63], v[60:61], off nt
	s_ashr_i32 s9, s8, 31
	s_lshl_b64 s[6:7], s[8:9], 1
	v_or_b32_e32 v64, s35, v8
	s_add_u32 s6, s36, s6
	v_ashrrev_i32_e32 v65, 31, v64
	s_addc_u32 s7, s33, s7
	v_lshlrev_b64 v[64:65], 11, v[64:65]
	v_lshl_add_u64 v[68:69], s[6:7], 0, v[2:3]
	v_or_b32_e32 v66, s35, v1
	v_lshl_add_u64 v[64:65], v[68:69], 0, v[64:65]
	v_ashrrev_i32_e32 v67, 31, v66
	v_lshlrev_b64 v[66:67], 11, v[66:67]
	v_lshl_add_u64 v[66:67], v[68:69], 0, v[66:67]
	s_add_i32 s15, s15, s42
	s_add_i32 s3, s3, s4
	s_add_i32 s12, s12, s13
	s_cmpk_gt_i32 s15, 0xbff
	s_waitcnt vmcnt(7)
	ds_write2_b32 v15, v30, v31 offset1:1
	ds_write2_b32 v15, v32, v33 offset0:2 offset1:3
	s_waitcnt vmcnt(6)
	ds_write2_b32 v16, v36, v37 offset1:1
	ds_write2_b32 v17, v38, v39 offset1:1
	s_waitcnt vmcnt(5)
	ds_write2_b32 v18, v40, v41 offset1:1
	ds_write2_b32 v19, v42, v43 offset1:1
	s_waitcnt vmcnt(4)
	ds_write2_b32 v20, v44, v45 offset1:1
	ds_write2_b32 v21, v46, v47 offset1:1
	s_waitcnt vmcnt(3)
	ds_write2_b32 v22, v48, v49 offset1:1
	ds_write2_b32 v23, v50, v51 offset1:1
	s_waitcnt vmcnt(2)
	ds_write2_b32 v24, v52, v53 offset1:1
	ds_write2_b32 v25, v54, v55 offset1:1
	s_waitcnt vmcnt(1)
	ds_write2_b32 v26, v56, v57 offset1:1
	ds_write2_b32 v27, v58, v59 offset1:1
	s_waitcnt vmcnt(0)
	ds_write2_b32 v28, v60, v61 offset1:1
	ds_write2_b32 v29, v62, v63 offset1:1
	s_waitcnt lgkmcnt(0)
	ds_read2_b32 v[32:33], v14 offset0:33 offset1:41
	ds_read2_b32 v[36:37], v14 offset1:8
	ds_read2_b32 v[38:39], v14 offset0:66 offset1:74
	ds_read2_b32 v[40:41], v14 offset0:99 offset1:107
	ds_read2_b32 v[42:43], v14 offset0:132 offset1:140
	ds_read2_b32 v[44:45], v14 offset0:165 offset1:173
	ds_read2_b32 v[46:47], v14 offset0:198 offset1:206
	ds_read2_b32 v[48:49], v14 offset0:231 offset1:239
	ds_read2_b32 v[50:51], v14 offset0:49 offset1:57
	ds_read2_b32 v[52:53], v14 offset0:16 offset1:24
	ds_read2_b32 v[54:55], v14 offset0:82 offset1:90
	ds_read2_b32 v[56:57], v14 offset0:115 offset1:123
	ds_read2_b32 v[58:59], v14 offset0:148 offset1:156
	ds_read2_b32 v[60:61], v14 offset0:181 offset1:189
	s_waitcnt lgkmcnt(12)
	v_cvt_pk_bf16_f32 v30, v36, v32
	s_waitcnt lgkmcnt(10)
	v_cvt_pk_bf16_f32 v31, v38, v40
	v_cvt_pk_bf16_f32 v36, v37, v33
	s_waitcnt lgkmcnt(8)
	v_cvt_pk_bf16_f32 v32, v42, v44
	s_waitcnt lgkmcnt(6)
	v_cvt_pk_bf16_f32 v33, v46, v48
	global_store_dwordx4 v[64:65], v[30:33], off sc1
	v_cvt_pk_bf16_f32 v37, v39, v41
	v_cvt_pk_bf16_f32 v38, v43, v45
	ds_read2_b32 v[40:41], v14 offset0:214 offset1:222
	ds_read2_b32 v[42:43], v14 offset0:247 offset1:255
	v_cvt_pk_bf16_f32 v39, v47, v49
	global_store_dwordx4 v[66:67], v[36:39], off sc1
	s_waitcnt lgkmcnt(6)
	v_cvt_pk_bf16_f32 v30, v52, v50
	s_waitcnt lgkmcnt(4)
	v_cvt_pk_bf16_f32 v31, v54, v56
	v_or_b32_e32 v36, s35, v6
	v_ashrrev_i32_e32 v37, 31, v36
	v_lshlrev_b64 v[36:37], 11, v[36:37]
	s_waitcnt lgkmcnt(2)
	v_cvt_pk_bf16_f32 v32, v58, v60
	s_waitcnt lgkmcnt(0)
	v_cvt_pk_bf16_f32 v33, v40, v42
	v_lshl_add_u64 v[36:37], v[68:69], 0, v[36:37]
	global_store_dwordx4 v[36:37], v[30:33], off sc1
	v_or_b32_e32 v36, s35, v7
	v_ashrrev_i32_e32 v37, 31, v36
	v_lshlrev_b64 v[36:37], 11, v[36:37]
	v_cvt_pk_bf16_f32 v30, v53, v51
	v_cvt_pk_bf16_f32 v31, v55, v57
	v_cvt_pk_bf16_f32 v32, v59, v61
	v_cvt_pk_bf16_f32 v33, v41, v43
	v_lshl_add_u64 v[36:37], v[68:69], 0, v[36:37]
	global_store_dwordx4 v[36:37], v[30:33], off sc1
	s_waitcnt lgkmcnt(0)
	s_cbranch_scc1 .LBB0_43

; #define GAS __attribute__((address_space(1)))
; #define LAS __attribute__((address_space(3)))
; __global__ void __launch_bounds__(NWAVES * 64, 2) fwd(Args args) {
;     ...
;         f32x4 wreg[8][4];
; #pragma unroll
;         for (int c = 0; c < 8; ++c)
; #pragma unroll
;             for (int j = 0; j < 4; ++j) wreg[c][j] = *(const LAS f32x4*)(w8 + c * 1024 + 256 * j + 4 * lane);
;         f32x4 vn[4];
;         if (gw < M) { const GAS f32x4* xr0 = (const GAS f32x4*)(x + (size_t)gw * D) + 2 * lane;
; #pragma unroll
;             for (int j = 0; j < 4; ++j) vn[j] = xr0[128 * (j >> 1) + (j & 1)]; }
;         for (int m = gw; m < M; m += NGW) {
;             f32x4 v[4];
; #pragma unroll
;             for (int j = 0; j < 4; ++j) v[j] = vn[j];
;             if (m + NGW < M) { const GAS f32x4* xr = (const GAS f32x4*)(x + (size_t)(m + NGW) * D) + 2 * lane;
; #pragma unroll
;                 for (int j = 0; j < 4; ++j) vn[j] = xr[128 * (j >> 1) + (j & 1)]; }
.LBB0_50:
	s_or_b64 exec, exec, s[6:7]
	s_waitcnt vmcnt(0) lgkmcnt(0)
	s_barrier
	s_and_saveexec_b64 s[6:7], s[96:97]
	s_cbranch_execz .Lts0_t
	v_mov_b32_e32 v1, 0x2c100
	v_mov_b32_e32 v2, 1
	global_atomic_add v1, v2, s[60:61]
.Lts0_t:
	s_or_b64 exec, exec, s[6:7]
	s_and_b32 s3, s2, 7
	s_lshl_b32 s3, s3, 3
	s_bfe_u32 s4, s2, 0x30003
	s_or_b32 s3, s3, s4
	s_lshl_b32 s3, s3, 8
	s_or_b32 s99, s3, 0xff
	s_lshr_b32 s4, s2, 6
	s_lshl_b32 s4, s4, 3
	s_or_b32 s3, s3, s4
	v_readlane_b32 s4, v240, 2
	s_mov_b32 s42, 32
	s_nop 0
	s_add_i32 s40, s3, s4
	s_cmp_le_i32 s40, s99
	s_cbranch_scc0 .LBB0_65
	s_ashr_i32 s41, s40, 31
	s_lshl_b64 s[6:7], s[40:41], 12
	s_add_u32 s8, s16, s6
	s_addc_u32 s9, s17, s7
	v_lshlrev_b32_e32 v38, 5, v234
	global_load_dwordx4 v[146:149], v38, s[8:9] nt
	global_load_dwordx4 v[154:157], v38, s[8:9] offset:16 nt
	global_load_dwordx4 v[150:153], v38, s[8:9] offset:2048 nt
	global_load_dwordx4 v[158:161], v38, s[8:9] offset:2064 nt
	v_mov_b32_e32 v39, 0
	v_lshl_add_u64 v[162:163], s[16:17], 0, v[38:39]
	s_lshl_b64 s[16:17], s[40:41], 5
	s_add_u32 s16, s60, s16
	v_mov_b32_e32 v35, v39
	s_addc_u32 s17, s61, s17
	v_lshl_add_u64 v[34:35], s[16:17], 0, v[34:35]
	s_mov_b64 s[16:17], 0x100000
	s_ashr_i32 s43, s42, 31
	v_and_b32_e32 v1, 32, v0
	v_lshl_add_u64 v[168:169], v[34:35], 0, s[16:17]
	s_lshl_b64 s[16:17], s[42:43], 5
	s_lshl_b64 s[20:21], s[40:41], 11
	v_cmp_eq_u32_e64 s[6:7], 0, v1
	v_and_b32_e32 v1, 16, v0
	s_add_u32 s20, s60, s20
	v_lshlrev_b32_e32 v36, 4, v234
	v_cmp_eq_u32_e64 s[8:9], 0, v1
	v_and_b32_e32 v1, 8, v0
	v_mov_b32_e32 v37, v39
	s_addc_u32 s21, s61, s21
	v_cmp_eq_u32_e64 s[10:11], 0, v1
	v_add_u32_e32 v2, -4, v8
	v_mov_b32_e32 v3, v39
	v_add_u32_e32 v1, 0, v36
	v_lshl_add_u64 v[34:35], s[20:21], 0, v[36:37]
	s_mov_b64 s[20:21], 0x4000400
	v_lshlrev_b64 v[2:3], 2, v[2:3]
	v_add_u32_e32 v126, 0x12000, v1
	v_lshl_add_u64 v[170:171], v[34:35], 0, s[20:21]
	v_cmp_eq_u32_e64 s[12:13], 0, v4
	v_lshl_add_u64 v[164:165], s[28:29], 0, v[2:3]
	v_lshl_add_u64 v[166:167], s[26:27], 0, v[2:3]
	ds_read_b128 v[2:5], v126 offset:31744
	ds_read_b128 v[6:9], v126 offset:30720
	ds_read_b128 v[10:13], v126 offset:29696
	ds_read_b128 v[14:17], v126 offset:28672
	ds_read_b128 v[18:21], v126 offset:27648
	ds_read_b128 v[22:25], v126 offset:26624
	ds_read_b128 v[26:29], v126 offset:25600
	ds_read_b128 v[30:33], v126 offset:24576
	ds_read_b128 v[34:37], v126 offset:23552
	ds_read_b128 v[38:41], v126 offset:22528
	ds_read_b128 v[42:45], v126 offset:21504
	ds_read_b128 v[46:49], v126 offset:20480
	ds_read_b128 v[50:53], v126 offset:19456
	ds_read_b128 v[54:57], v126 offset:18432
	ds_read_b128 v[58:61], v126 offset:17408
	ds_read_b128 v[62:65], v126 offset:16384
	ds_read_b128 v[66:69], v126 offset:15360
	ds_read_b128 v[70:73], v126 offset:14336
	ds_read_b128 v[74:77], v126 offset:13312
	ds_read_b128 v[78:81], v126 offset:12288
	ds_read_b128 v[82:85], v126 offset:11264
	ds_read_b128 v[86:89], v126 offset:10240
	ds_read_b128 v[90:93], v126 offset:9216
	ds_read_b128 v[94:97], v126 offset:8192
	ds_read_b128 v[98:101], v126 offset:7168
	ds_read_b128 v[102:105], v126 offset:6144
	ds_read_b128 v[106:109], v126 offset:5120
	ds_read_b128 v[110:113], v126 offset:4096
	ds_read_b128 v[114:117], v126 offset:3072
	ds_read_b128 v[118:121], v126 offset:2048
	ds_read_b128 v[122:125], v126 offset:1024
	ds_read_b128 v[126:129], v126
	v_mbcnt_lo_u32_b32 v1, -1, 0
	v_cmp_lt_u32_e64 s[14:15], 31, v234
	s_lshl_b64 s[20:21], s[42:43], 11
	v_mbcnt_hi_u32_b32 v1, -1, v1
	s_mov_b32 s3, 0x41a00000
	s_mov_b32 s4, 0x3fb8aa3b
	s_mov_b32 s33, 0xc2ce8ed0
	s_mov_b32 s35, 0x42b17218
	s_mov_b32 s36, 0x7f800000
	s_mov_b32 s37, 0x3f2aaaab
	v_mov_b32_e32 v174, 0x3ecc95a3
	s_mov_b32 s43, 0x3f317218
	s_mov_b32 s48, 0x33800000
	s_mov_b32 s49, 0xbfb8aa3b
	s_mov_b32 s50, 0x42ce8ed0
	s_mov_b32 s51, 0xc2b17218
	v_mov_b32_e32 v175, 0x7f800000
	v_mov_b32_e32 v172, 0x3f317218
	s_mov_b64 s[44:45], exec
	s_and_b64 exec, exec, s[14:15]
	global_load_dword v241, v[164:165], off
	global_load_dword v242, v[166:167], off
	s_mov_b64 exec, s[44:45]
	s_branch .LBB0_54
.LBB0_52:
	s_or_b64 exec, exec, s[44:45]
	global_store_dword v[168:169], v147, off sc1

; #define GAS __attribute__((address_space(1)))
; __global__ void __launch_bounds__(NWAVES * 64, 2) fwd(Args args) {
;     ...
;         for (int m = gw; m < M; m += NGW) {
;             f32x4 v[4];
; #pragma unroll
;             for (int j = 0; j < 4; ++j) v[j] = vn[j];
;             if (m + NGW < M) { const GAS f32x4* xr = (const GAS f32x4*)(x + (size_t)(m + NGW) * D) + 2 * lane;
; #pragma unroll
;                 for (int j = 0; j < 4; ++j) vn[j] = xr[128 * (j >> 1) + (j & 1)]; }
.LBB0_54:
	s_add_i32 s40, s40, s42
	s_cmp_gt_i32 s40, s99
	s_cselect_b64 s[26:27], -1, 0
	s_cmp_le_i32 s40, s99
	s_cbranch_scc0 .LBB0_56
	s_ashr_i32 s41, s40, 31
	s_lshl_b64 s[28:29], s[40:41], 12
	v_lshl_add_u64 v[142:143], v[162:163], 0, s[28:29]
	global_load_dwordx4 v[130:133], v[142:143], off nt
	global_load_dwordx4 v[134:137], v[142:143], off offset:16 nt
	global_load_dwordx4 v[138:141], v[142:143], off offset:2048 nt
	s_nop 0
	global_load_dwordx4 v[142:145], v[142:143], off offset:2064 nt
	s_branch .LBB0_57

; __global__ void __launch_bounds__(NWAVES * 64, 2) fwd(Args args) {
;     ...
;             float acc[8];
; #pragma unroll
;             for (int c = 0; c < 8; ++c) { float a = 0.f;
; #pragma unroll
;                 for (int j = 0; j < 4; ++j) { const f32x4 w = wreg[c][j]; a += v[j].x * w.x + v[j].y * w.y + v[j].z * w.z + v[j].w * w.w; }
;                 acc[c] = a; }
;             float a4[4], a2[2], a1;
;             { const bool hi = (lane & 32) != 0;
; #pragma unroll
;               for (int i = 0; i < 4; ++i) { const float send = hi ? acc[i] : acc[4 + i], keep = hi ? acc[4 + i] : acc[i]; a4[i] = keep + __shfl_xor(send, 32); } }
;             { const bool hi = (lane & 16) != 0;
; #pragma unroll
;               for (int i = 0; i < 2; ++i) { const float send = hi ? a4[i] : a4[2 + i], keep = hi ? a4[2 + i] : a4[i]; a2[i] = keep + __shfl_xor(send, 16); } }
;             { const bool hi = (lane & 8) != 0; const float send = hi ? a2[0] : a2[1], keep = hi ? a2[1] : a2[0]; a1 = keep + __shfl_xor(send, 8); }
.LBB0_57:
	s_waitcnt vmcnt(7) lgkmcnt(0)
	v_mul_f32_e32 v173, v147, v127
	v_fmac_f32_e32 v173, v146, v126
	s_waitcnt vmcnt(6)
	v_mul_f32_e32 v176, v155, v123
	v_fmac_f32_e32 v173, v148, v128
	v_fmac_f32_e32 v176, v154, v122
	v_fmac_f32_e32 v173, v149, v129
	v_fmac_f32_e32 v176, v156, v124
	v_add_f32_e32 v173, 0, v173
	v_fmac_f32_e32 v176, v157, v125
	v_add_f32_e32 v173, v173, v176
	s_waitcnt vmcnt(5)
	v_mul_f32_e32 v176, v151, v119
	v_fmac_f32_e32 v176, v150, v118
	v_fmac_f32_e32 v176, v152, v120
	v_fmac_f32_e32 v176, v153, v121
	v_add_f32_e32 v173, v173, v176
	s_waitcnt vmcnt(4)
	v_mul_f32_e32 v176, v159, v115
	v_fmac_f32_e32 v176, v158, v114
	v_fmac_f32_e32 v176, v160, v116
	v_fmac_f32_e32 v176, v161, v117
	v_add_f32_e32 v173, v173, v176
	v_mul_f32_e32 v176, v147, v111
	v_fmac_f32_e32 v176, v146, v110
	v_mul_f32_e32 v177, v155, v107
	v_fmac_f32_e32 v176, v148, v112
	v_fmac_f32_e32 v177, v154, v106
	v_fmac_f32_e32 v176, v149, v113
	v_fmac_f32_e32 v177, v156, v108
	v_add_f32_e32 v176, 0, v176
	v_fmac_f32_e32 v177, v157, v109
	v_add_f32_e32 v176, v176, v177
	v_mul_f32_e32 v177, v151, v103
	v_fmac_f32_e32 v177, v150, v102
	v_fmac_f32_e32 v177, v152, v104
	v_fmac_f32_e32 v177, v153, v105
	v_add_f32_e32 v176, v176, v177
	v_mul_f32_e32 v177, v159, v99
	v_fmac_f32_e32 v177, v158, v98
	v_fmac_f32_e32 v177, v160, v100
	v_fmac_f32_e32 v177, v161, v101
	v_add_f32_e32 v176, v176, v177
	v_mul_f32_e32 v177, v147, v95
	v_fmac_f32_e32 v177, v146, v94
	v_mul_f32_e32 v178, v155, v91
	v_fmac_f32_e32 v177, v148, v96
	v_fmac_f32_e32 v178, v154, v90
	v_fmac_f32_e32 v177, v149, v97
	v_fmac_f32_e32 v178, v156, v92
	v_add_f32_e32 v177, 0, v177
	v_fmac_f32_e32 v178, v157, v93
	v_add_f32_e32 v177, v177, v178
	v_mul_f32_e32 v178, v151, v87
	v_fmac_f32_e32 v178, v150, v86
	v_fmac_f32_e32 v178, v152, v88
	v_fmac_f32_e32 v178, v153, v89
	v_add_f32_e32 v177, v177, v178
	v_mul_f32_e32 v178, v159, v83
	v_fmac_f32_e32 v178, v158, v82
	v_fmac_f32_e32 v178, v160, v84
	v_fmac_f32_e32 v178, v161, v85
	v_add_f32_e32 v177, v177, v178
	v_mul_f32_e32 v178, v147, v79
	v_fmac_f32_e32 v178, v146, v78
	v_mul_f32_e32 v179, v155, v75
	v_fmac_f32_e32 v178, v148, v80
	v_fmac_f32_e32 v179, v154, v74
	v_fmac_f32_e32 v178, v149, v81
	v_fmac_f32_e32 v179, v156, v76
	v_add_f32_e32 v178, 0, v178
	v_fmac_f32_e32 v179, v157, v77
	v_add_f32_e32 v178, v178, v179
	v_mul_f32_e32 v179, v151, v71
	v_fmac_f32_e32 v179, v150, v70
	v_fmac_f32_e32 v179, v152, v72
	v_fmac_f32_e32 v179, v153, v73
	v_add_f32_e32 v178, v178, v179
	v_mul_f32_e32 v179, v159, v67
	v_fmac_f32_e32 v179, v158, v66
	v_fmac_f32_e32 v179, v160, v68
	v_fmac_f32_e32 v179, v161, v69
	v_add_f32_e32 v178, v178, v179
	v_mul_f32_e32 v179, v147, v63
	v_fmac_f32_e32 v179, v146, v62
	v_mul_f32_e32 v180, v155, v59
	v_fmac_f32_e32 v179, v148, v64
	v_fmac_f32_e32 v180, v154, v58
	v_fmac_f32_e32 v179, v149, v65
	v_fmac_f32_e32 v180, v156, v60
	v_add_f32_e32 v179, 0, v179
	v_fmac_f32_e32 v180, v157, v61
	v_add_f32_e32 v179, v179, v180
	v_mul_f32_e32 v180, v151, v55
	v_fmac_f32_e32 v180, v150, v54
	v_fmac_f32_e32 v180, v152, v56
	v_fmac_f32_e32 v180, v153, v57
	v_add_f32_e32 v179, v179, v180
	v_mul_f32_e32 v180, v159, v51
	v_fmac_f32_e32 v180, v158, v50
	v_fmac_f32_e32 v180, v160, v52
	v_fmac_f32_e32 v180, v161, v53
	v_add_f32_e32 v179, v179, v180
	v_mul_f32_e32 v180, v147, v47
	v_fmac_f32_e32 v180, v146, v46
	v_mul_f32_e32 v181, v155, v43
	v_fmac_f32_e32 v180, v148, v48
	v_fmac_f32_e32 v181, v154, v42
	v_fmac_f32_e32 v180, v149, v49
	v_fmac_f32_e32 v181, v156, v44
	v_add_f32_e32 v180, 0, v180
	v_fmac_f32_e32 v181, v157, v45
	v_add_f32_e32 v180, v180, v181
	v_mul_f32_e32 v181, v151, v39
	v_fmac_f32_e32 v181, v150, v38
	v_fmac_f32_e32 v181, v152, v40
	v_fmac_f32_e32 v181, v153, v41
	v_add_f32_e32 v180, v180, v181
	v_mul_f32_e32 v181, v159, v35
	v_fmac_f32_e32 v181, v158, v34
	v_fmac_f32_e32 v181, v160, v36
	v_fmac_f32_e32 v181, v161, v37
	v_add_f32_e32 v180, v180, v181
	v_mul_f32_e32 v181, v147, v31
	v_fmac_f32_e32 v181, v146, v30
	v_mul_f32_e32 v182, v155, v27
	v_fmac_f32_e32 v181, v148, v32
	v_fmac_f32_e32 v182, v154, v26
	v_fmac_f32_e32 v181, v149, v33
	v_fmac_f32_e32 v182, v156, v28
	v_add_f32_e32 v181, 0, v181
	v_fmac_f32_e32 v182, v157, v29
	v_add_f32_e32 v181, v181, v182
	v_mul_f32_e32 v182, v151, v23
	v_fmac_f32_e32 v182, v150, v22
	v_fmac_f32_e32 v182, v152, v24
	v_fmac_f32_e32 v182, v153, v25
	v_add_f32_e32 v181, v181, v182
	v_mul_f32_e32 v182, v159, v19
	v_fmac_f32_e32 v182, v158, v18
	v_fmac_f32_e32 v182, v160, v20
	v_fmac_f32_e32 v182, v161, v21
	v_add_f32_e32 v181, v181, v182
	v_mul_f32_e32 v182, v147, v15
	v_fmac_f32_e32 v182, v146, v14
	v_mul_f32_e32 v183, v155, v11
	v_fmac_f32_e32 v182, v148, v16
	v_fmac_f32_e32 v183, v154, v10
	v_fmac_f32_e32 v182, v149, v17
	v_fmac_f32_e32 v183, v156, v12
	v_add_f32_e32 v182, 0, v182
	v_fmac_f32_e32 v183, v157, v13
	v_add_f32_e32 v182, v182, v183
	v_mul_f32_e32 v183, v151, v7
	v_fmac_f32_e32 v183, v150, v6
	v_fmac_f32_e32 v183, v152, v8
	v_fmac_f32_e32 v183, v153, v9
	v_and_b32_e32 v186, 64, v1
	v_add_f32_e32 v182, v182, v183
	v_mul_f32_e32 v183, v159, v3
	v_xor_b32_e32 v185, 32, v1
	v_add_u32_e32 v186, 64, v186
	v_fmac_f32_e32 v183, v158, v2
	v_cmp_lt_i32_e32 vcc, v185, v186
	v_fmac_f32_e32 v183, v160, v4
	v_cndmask_b32_e64 v187, v173, v179, s[6:7]
	v_cndmask_b32_e32 v185, v1, v185, vcc
	v_lshlrev_b32_e32 v185, 2, v185
	v_fmac_f32_e32 v183, v161, v5
	v_cndmask_b32_e64 v173, v179, v173, s[6:7]
	v_cndmask_b32_e64 v179, v176, v180, s[6:7]
	v_add_f32_e32 v182, v182, v183
	ds_bpermute_b32 v179, v185, v179
	v_cndmask_b32_e64 v176, v180, v176, s[6:7]
	v_cndmask_b32_e64 v180, v177, v181, s[6:7]
	v_cndmask_b32_e64 v183, v178, v182, s[6:7]
	ds_bpermute_b32 v187, v185, v187
	ds_bpermute_b32 v180, v185, v180
	ds_bpermute_b32 v183, v185, v183
	s_waitcnt lgkmcnt(3)
; #define GAS __attribute__((address_space(1)))
; __device__ __forceinline__ unsigned pk2(float lo, float hi) { const f32x2_t v = {lo, hi}; return __builtin_bit_cast(unsigned, __builtin_convertvector(v, bf16x2_t)); }
; __global__ void __launch_bounds__(NWAVES * 64, 2) fwd(Args args) {
;     ...
;             GAS v4u* o16 = (GAS v4u*)(XB + (size_t)m * D) + lane;
; #pragma unroll
;             for (int jj = 0; jj < 2; ++jj) { v4u o; o.x = pk2(v[2 * jj].x, v[2 * jj].y); o.y = pk2(v[2 * jj].z, v[2 * jj].w); o.z = pk2(v[2 * jj + 1].x, v[2 * jj + 1].y); o.w = pk2(v[2 * jj + 1].z, v[2 * jj + 1].w); o16[64 * jj] = o; }
;             float acc[8];
; #pragma unroll
;             for (int c = 0; c < 8; ++c) { float a = 0.f;
; #pragma unroll
;                 for (int j = 0; j < 4; ++j) { const f32x4 w = wreg[c][j]; a += v[j].x * w.x + v[j].y * w.y + v[j].z * w.z + v[j].w * w.w; }
;                 acc[c] = a; }
;             float a4[4], a2[2], a1;
;             { const bool hi = (lane & 32) != 0;
; #pragma unroll
;               for (int i = 0; i < 4; ++i) { const float send = hi ? acc[i] : acc[4 + i], keep = hi ? acc[4 + i] : acc[i]; a4[i] = keep + __shfl_xor(send, 32); } }
;             { const bool hi = (lane & 16) != 0;
; #pragma unroll
;               for (int i = 0; i < 2; ++i) { const float send = hi ? a4[i] : a4[2 + i], keep = hi ? a4[2 + i] : a4[i]; a2[i] = keep + __shfl_xor(send, 16); } }
;             { const bool hi = (lane & 8) != 0; const float send = hi ? a2[0] : a2[1], keep = hi ? a2[1] : a2[0]; a1 = keep + __shfl_xor(send, 8); }
;             a1 += __shfl_xor(a1, 4); a1 += __shfl_xor(a1, 2); a1 += __shfl_xor(a1, 1);
;             if ((lane & 7) == 0) { const int cc = lane >> 3; float r;
;                 if (cc < 4) r = 1.f / (1.f + expf(-a1));
;                 else { const int h = cc - 4; const float z = a1 + dt_bias[h]; const float sp = z > 20.f ? z : log1pf(expf(z)); r = -expf(A_log[h]) * sp; }
;                 GBT[(size_t)m * 8 + cc] = r;
	v_add_f32_e32 v176, v176, v179
	v_xor_b32_e32 v179, 16, v1
	v_cndmask_b32_e64 v177, v181, v177, s[6:7]
	v_cndmask_b32_e64 v178, v182, v178, s[6:7]
	v_cmp_lt_i32_e32 vcc, v179, v186
	s_waitcnt lgkmcnt(2)
	v_add_f32_e32 v173, v173, v187
	s_waitcnt lgkmcnt(1)
	v_add_f32_e32 v177, v177, v180
	s_waitcnt lgkmcnt(0)
	v_add_f32_e32 v178, v178, v183
	v_cndmask_b32_e32 v179, v1, v179, vcc
	v_lshlrev_b32_e32 v179, 2, v179
	v_cndmask_b32_e64 v180, v173, v177, s[8:9]
	v_cndmask_b32_e64 v181, v176, v178, s[8:9]
	ds_bpermute_b32 v180, v179, v180
	ds_bpermute_b32 v179, v179, v181
	v_cndmask_b32_e64 v176, v178, v176, s[8:9]
	v_xor_b32_e32 v178, 8, v1
	v_cndmask_b32_e64 v173, v177, v173, s[8:9]
	v_cmp_lt_i32_e32 vcc, v178, v186
	s_waitcnt lgkmcnt(1)
	v_add_f32_e32 v173, v173, v180
	s_waitcnt lgkmcnt(0)
	v_add_f32_e32 v176, v176, v179
	v_cndmask_b32_e32 v178, v1, v178, vcc
	v_cndmask_b32_e64 v177, v173, v176, s[10:11]
	v_lshlrev_b32_e32 v178, 2, v178
	ds_bpermute_b32 v177, v178, v177
	v_cndmask_b32_e64 v173, v176, v173, s[10:11]
	v_xor_b32_e32 v176, 4, v1
	v_cmp_lt_i32_e32 vcc, v176, v186
	s_waitcnt lgkmcnt(0)
	v_add_f32_e32 v173, v173, v177
	v_cvt_pk_bf16_f32 v146, v146, v147
	v_cndmask_b32_e32 v176, v1, v176, vcc
	v_lshlrev_b32_e32 v176, 2, v176
	ds_bpermute_b32 v176, v176, v173
	v_cvt_pk_bf16_f32 v147, v148, v149
	v_xor_b32_e32 v148, 2, v1
	v_cmp_lt_i32_e32 vcc, v148, v186
	v_cvt_pk_bf16_f32 v149, v156, v157
	s_waitcnt lgkmcnt(0)
	v_add_f32_e32 v173, v173, v176
	v_cndmask_b32_e32 v148, v1, v148, vcc
	v_lshlrev_b32_e32 v148, 2, v148
	ds_bpermute_b32 v176, v148, v173
	v_cvt_pk_bf16_f32 v148, v154, v155
	global_store_dwordx4 v[170:171], v[146:149], off offset:-1024 sc1
	s_nop 1
	v_xor_b32_e32 v147, 1, v1
	v_cmp_lt_i32_e32 vcc, v147, v186
	s_waitcnt lgkmcnt(0)
	v_add_f32_e32 v146, v173, v176
	v_cvt_pk_bf16_f32 v148, v150, v151
	v_cndmask_b32_e32 v147, v1, v147, vcc
	v_lshlrev_b32_e32 v147, 2, v147
	ds_bpermute_b32 v147, v147, v146
	v_cvt_pk_bf16_f32 v149, v152, v153
	v_cvt_pk_bf16_f32 v150, v158, v159
	v_cvt_pk_bf16_f32 v151, v160, v161
	global_store_dwordx4 v[170:171], v[148:151], off sc1
	s_and_saveexec_b64 s[28:29], s[12:13]
	s_cbranch_execz .LBB0_53
	s_waitcnt lgkmcnt(0)
	v_add_f32_e32 v146, v146, v147
	s_and_saveexec_b64 s[44:45], s[14:15]
	s_xor_b64 s[44:45], exec, s[44:45]
	s_cbranch_execz .LBB0_62
	v_add_f32_e32 v146, v146, v241
	v_cmp_nlt_f32_e32 vcc, s3, v146
	s_and_saveexec_b64 s[46:47], vcc
	s_cbranch_execz .LBB0_61
; __global__ void __launch_bounds__(NWAVES * 64, 2) fwd(Args args) {
;     ...
;                 if (cc < 4) r = 1.f / (1.f + expf(-a1));
;                 else { const int h = cc - 4; const float z = a1 + dt_bias[h]; const float sp = z > 20.f ? z : log1pf(expf(z)); r = -expf(A_log[h]) * sp; }
;                 GBT[(size_t)m * 8 + cc] = r;
	v_mul_f32_e32 v147, 0x3fb8aa3b, v146
	v_rndne_f32_e32 v148, v147
	v_sub_f32_e32 v149, v147, v148
	v_fma_f32 v147, v146, s4, -v147
	v_fmac_f32_e32 v147, 0x32a5705f, v146
	v_add_f32_e32 v147, v149, v147
	v_cvt_i32_f32_e32 v148, v148
	v_exp_f32_e32 v147, v147
	v_cmp_ngt_f32_e32 vcc, s33, v146
	v_ldexp_f32 v147, v147, v148
	s_nop 0
	v_cndmask_b32_e32 v147, 0, v147, vcc
	v_cmp_nlt_f32_e32 vcc, s35, v146
	s_nop 1
	v_cndmask_b32_e32 v160, v175, v147, vcc
	v_add_f32_e32 v148, 1.0, v160
	v_add_f32_e32 v146, -1.0, v148
	v_sub_f32_e32 v147, v146, v148
	v_add_f32_e32 v147, 1.0, v147
	v_sub_f32_e32 v146, v160, v146
	v_add_f32_e32 v149, v146, v147
	v_frexp_mant_f32_e32 v150, v148
	v_cvt_f64_f32_e32 v[146:147], v148
	v_frexp_exp_i32_f64_e32 v146, v[146:147]
	v_cmp_gt_f32_e32 vcc, s37, v150
	s_nop 1
	v_subbrev_co_u32_e32 v154, vcc, 0, v146, vcc
	v_sub_u32_e32 v146, 0, v154
	v_ldexp_f32 v147, v148, v146
	v_add_f32_e32 v148, -1.0, v147
	v_add_f32_e32 v150, 1.0, v147
	v_ldexp_f32 v146, v149, v146
	v_add_f32_e32 v149, 1.0, v148
	v_add_f32_e32 v151, -1.0, v150
	v_sub_f32_e32 v149, v147, v149
	v_sub_f32_e32 v147, v147, v151
	v_add_f32_e32 v149, v146, v149
	v_add_f32_e32 v146, v146, v147
	v_add_f32_e32 v155, v150, v146
	v_rcp_f32_e32 v157, v155
	v_sub_f32_e32 v147, v150, v155
	v_add_f32_e32 v156, v146, v147
	v_add_f32_e32 v147, v148, v149
	v_mul_f32_e32 v159, v147, v157
	v_sub_f32_e32 v146, v148, v147
	v_mul_f32_e32 v148, v155, v159
	v_fma_f32 v150, v159, v155, -v148
	v_fmac_f32_e32 v150, v159, v156
	v_add_f32_e32 v158, v149, v146
	v_add_f32_e32 v146, v148, v150
	v_sub_f32_e32 v149, v147, v146
	v_pk_add_f32 v[152:153], v[146:147], v[148:149] neg_lo:[0,1] neg_hi:[0,1]
	v_mov_b32_e32 v151, v146
	v_pk_add_f32 v[146:147], v[152:153], v[150:151] neg_lo:[0,1] neg_hi:[0,1]
	v_cmp_neq_f32_e32 vcc, s36, v160
	v_add_f32_e32 v147, v158, v147
	v_add_f32_e32 v146, v146, v147
	v_add_f32_e32 v147, v149, v146
	v_mul_f32_e32 v158, v157, v147
	v_mul_f32_e32 v148, v155, v158
	v_fma_f32 v150, v158, v155, -v148
	v_fmac_f32_e32 v150, v158, v156
	v_sub_f32_e32 v149, v149, v147
	v_add_f32_e32 v155, v146, v149
	v_add_f32_e32 v146, v148, v150
	v_sub_f32_e32 v149, v147, v146
	v_pk_add_f32 v[152:153], v[146:147], v[148:149] neg_lo:[0,1] neg_hi:[0,1]
	v_mov_b32_e32 v151, v146
	v_pk_add_f32 v[146:147], v[152:153], v[150:151] neg_lo:[0,1] neg_hi:[0,1]
	s_nop 0
	v_add_f32_e32 v147, v155, v147
	v_add_f32_e32 v146, v146, v147
	v_add_f32_e32 v147, v159, v158
	v_add_f32_e32 v146, v149, v146
	v_sub_f32_e32 v148, v147, v159
	v_mul_f32_e32 v146, v157, v146
	v_sub_f32_e32 v148, v158, v148
	v_add_f32_e32 v148, v148, v146
	v_add_f32_e32 v150, v147, v148
	v_mul_f32_e32 v151, v150, v150
	v_fmamk_f32 v146, v151, 0x3e9b6dac, v174
	v_fmaak_f32 v173, v151, v146, 0x3f2aaada
	v_cvt_f32_i32_e32 v146, v154
	v_sub_f32_e32 v147, v150, v147
	v_sub_f32_e32 v147, v148, v147
	v_ldexp_f32 v152, v147, 1
	v_mul_f32_e32 v147, v150, v151
	v_ldexp_f32 v149, v150, 1
	v_pk_mul_f32 v[150:151], v[146:147], v[172:173]
	s_nop 0
	v_fma_f32 v148, v146, s43, -v150
	v_fmac_f32_e32 v148, 0xb102e308, v146
	v_pk_add_f32 v[146:147], v[150:151], v[148:149]
	s_nop 0
	v_sub_f32_e32 v149, v147, v149
	v_sub_f32_e32 v149, v151, v149
	v_add_f32_e32 v153, v152, v149
	v_mov_b32_e32 v152, v150
	v_pk_add_f32 v[150:151], v[146:147], v[150:151] neg_lo:[0,1] neg_hi:[0,1]
	v_pk_add_f32 v[154:155], v[146:147], v[152:153]
	v_mov_b32_e32 v149, v146
	v_mov_b32_e32 v151, v155
	v_pk_add_f32 v[156:157], v[148:149], v[150:151] neg_lo:[0,1] neg_hi:[0,1]
	v_pk_add_f32 v[148:149], v[148:149], v[150:151]
	v_mov_b32_e32 v152, v153
	v_pk_add_f32 v[150:151], v[148:149], v[146:147] op_sel:[1,0] op_sel_hi:[0,1] neg_lo:[0,1] neg_hi:[0,1]
	v_pk_add_f32 v[158:159], v[154:155], v[150:151] op_sel_hi:[1,0] neg_lo:[0,1] neg_hi:[0,1]
	v_mov_b32_e32 v154, v155
	v_mov_b32_e32 v155, v149
	v_pk_mov_b32 v[150:151], v[146:147], v[150:151] op_sel:[1,0]
	v_mov_b32_e32 v153, v146
	v_pk_add_f32 v[150:151], v[154:155], v[150:151] neg_lo:[0,1] neg_hi:[0,1]
	v_mov_b32_e32 v158, v156
	v_pk_add_f32 v[146:147], v[152:153], v[150:151] neg_lo:[0,1] neg_hi:[0,1]
	v_mov_b32_e32 v157, v149
	v_pk_add_f32 v[150:151], v[158:159], v[146:147]
	s_nop 0
	v_pk_add_f32 v[152:153], v[150:151], v[150:151] op_sel:[0,1] op_sel_hi:[1,0]
	s_nop 0
	v_pk_add_f32 v[148:149], v[148:149], v[152:153] op_sel:[1,0] op_sel_hi:[0,1]
	v_mov_b32_e32 v151, v148
	v_pk_add_f32 v[154:155], v[150:151], v[156:157] neg_lo:[0,1] neg_hi:[0,1]
	v_mov_b32_e32 v147, v152
	v_sub_f32_e32 v149, v150, v154
	v_pk_add_f32 v[146:147], v[146:147], v[154:155] neg_lo:[0,1] neg_hi:[0,1]
	v_sub_f32_e32 v149, v156, v149
	v_add_f32_e32 v146, v146, v149
	v_add_f32_e32 v146, v146, v147
	v_add_f32_e32 v146, v148, v146
	v_cndmask_b32_e32 v146, v175, v146, vcc
	v_cmp_lt_f32_e64 vcc, |v160|, s48
	s_nop 1
	v_cndmask_b32_e32 v146, v146, v160, vcc

; __device__ __forceinline__ unsigned xb_ld(unsigned* p)              { return __hip_atomic_load(p, __ATOMIC_RELAXED, __HIP_MEMORY_SCOPE_AGENT); }
; __device__ __forceinline__ unsigned xb_add(unsigned* p, unsigned v) { return __hip_atomic_fetch_add(p, v, __ATOMIC_RELAXED, __HIP_MEMORY_SCOPE_AGENT); }
; #define XB_SPIN(cond, bar) do { unsigned _sp = 0; while (cond) { __builtin_amdgcn_s_sleep(1); \
;     if ((++_sp & 255u) == 0u) { if (xb_ld(&(bar)[XB_TMO])) break; if (_sp > XB_SPIN_CAP) { atomicAdd(&(bar)[XB_TMO], 1u); break; } } } } while (0)
; #define BOTH(k) (IN(k) && (k) + 1 < hi)
; #define GRID_BAR() xcd_barrier(bar)
; __device__ __forceinline__ void team_barrier(unsigned* ctr, unsigned target, unsigned* bar) {
;     asm volatile("s_waitcnt vmcnt(0)" ::: "memory");
;     __syncthreads();
;     if (threadIdx.x == 0) {
;         __builtin_amdgcn_s_waitcnt(0);
;         (void)xb_add(ctr, 1u);
;         asm volatile("buffer_inv sc1" ::: "memory");
;         XB_SPIN(xb_ld(ctr) < target, bar);
;         asm volatile("s_waitcnt vmcnt(0)" ::: "memory");
;     }
;     __syncthreads();
; }
; __global__ void __launch_bounds__(NWAVES * 64, 2) fwd(Args args) {
;     ...
;         if (BOTH(0)) GRID_BAR();
.LBB0_65:
	s_cmp_gt_i32 s57, 1
	s_barrier
	s_cbranch_scc0 .LBB0_115
	s_waitcnt vmcnt(0)
	s_barrier
	s_and_saveexec_b64 s[6:7], s[96:97]
	s_cbranch_execz .Lts0_join
	s_and_b32 s3, s2, 7
	s_lshl_b32 s3, s3, 3
	s_bfe_u32 s4, s2, 0x30003
	s_or_b32 s3, s3, s4
	s_lshl_b32 s3, s3, 7
	s_add_u32 s8, s60, s3
	s_addc_u32 s9, s61, 0
	s_add_u32 s8, s8, 0x2d000
	s_addc_u32 s9, s9, 0
	v_mov_b32_e32 v1, 0
	v_mov_b32_e32 v2, 1
	v_mov_b32_e32 v3, 0x2c100
	v_mov_b32_e32 v5, 0
	global_atomic_add v1, v2, s[8:9]
.Lts0_spin:
	global_load_dword v6, v1, s[8:9] sc1
	global_load_dword v7, v3, s[60:61] sc1
	s_waitcnt vmcnt(0)
	v_lshrrev_b32_e32 v6, 2, v6
	v_lshrrev_b32_e32 v7, 8, v7
	v_min_u32_e32 v6, v6, v7
	v_cmp_ne_u32_e32 vcc, 0, v6
	s_cbranch_vccnz .Lts0_done
	s_sleep 1
	v_add_u32_e32 v5, 1, v5
	v_cmp_gt_u32_e32 vcc, 0x4000, v5
	s_cbranch_vccnz .Lts0_spin
	global_atomic_add v1, v2, s[58:59] offset:512
